# gm spatial-gating loop: next iteration's gate/gain loads prefetched into spare VGPRs during the previous iteration's epilogue
# speedup vs baseline: 1.0010x; 1.0010x over previous
; DI unsigned cvt_pk_bf16(float lo, float hi) { unsigned r; asm volatile("v_cvt_pk_bf16_f32 %0, %1, %2" : "=v"(r) : "v"(lo), "v"(hi)); return r; }
; DI float bf_lo(unsigned w) { return __uint_as_float(w << 16); }
; DI float bf_hi(unsigned w) { return __uint_as_float(w & 0xffff0000u); }
; DI void gm_unit(const Ctx& cx, const bf16_t* __restrict__ PG, bf16_t* __restrict__ Ogm, const float* __restrict__ gvn, const float* __restrict__ ws, const float* __restrict__ bs, int unit, LAS unsigned char* lds) {
;     ...
;   for (int gi = 0; gi < 4; ++gi) {
;     const int g = gh * 4 + gi;
;     u32x4 vraw[4];
; #pragma unroll
;     for (int it = 0; it < 4; ++it) vraw[it] = *(const u32x4*)(PG + (size_t)(tok0 + srow + 32 * it) * PGW + 4096 + g * 128 + chn * 8);
;     const f32x4 g0 = *(const f32x4*)(gvn + g * 128 + chn * 8), g1 = *(const f32x4*)(gvn + g * 128 + chn * 8 + 4);
;     ...
;     bf16_t* op = Ogm + (size_t)(tok0 + t) * 1024 + g * 128;
; #pragma unroll
;     for (int e = 0; e < 2; ++e)
; #pragma unroll
;       for (int qd = 0; qd < 4; ++qd) { const int d0 = (2 * dbp + e) * 32 + 8 * qd + 4 * h; const u32x2 u2 = uu[e][qd];
;         u32x2 w;
;         w.x = cvt_pk_bf16(bf_lo(u2.x) * (acc[e][4 * qd] + bias), bf_hi(u2.x) * (acc[e][4 * qd + 1] + bias));
;         w.y = cvt_pk_bf16(bf_lo(u2.y) * (acc[e][4 * qd + 2] + bias), bf_hi(u2.y) * (acc[e][4 * qd + 3] + bias));
;         *(u32x2*)(op + d0) = w; }
;     __syncthreads();
.LBB0_915:
	s_or_b64 exec, exec, s[22:23]
	v_add_u32_e32 v0, s24, v88
	v_mad_i64_i32 v[102:103], s[22:23], v0, s33, v[96:97]
	v_add_u32_e32 v0, s24, v140
	v_mad_i64_i32 v[104:105], s[22:23], v0, s33, v[96:97]
	v_add_u32_e32 v0, s24, v141
	v_mad_i64_i32 v[106:107], s[22:23], v0, s33, v[96:97]
	v_add_u32_e32 v0, s24, v142
	s_bfe_u32 s36, s10, 0x10002
	v_mad_i64_i32 v[108:109], s[22:23], v0, s33, v[96:97]
	s_lshl_b32 s22, s36, 11
	s_mov_b32 s23, s13
	s_bfe_u32 s37, s25, 0x20006
	s_lshl_b32 s12, s36, 10
	v_lshl_add_u64 v[110:111], v[100:101], 0, s[22:23]
	s_ashr_i32 s23, s25, 8
	s_lshl_b32 s25, s37, 5
	s_cmp_gt_u32 s37, 1
	s_cselect_b64 s[38:39], -1, 0
	s_add_i32 s24, s25, s24
	s_lshl_b32 s22, s23, 6
	v_add_u32_e32 v0, s24, v216
	s_waitcnt lgkmcnt(0)
	v_ashrrev_i32_e32 v1, 31, v0
	v_or_b32_e32 v4, s22, v178
	s_lshl_b32 s41, s23, 7
	s_ashr_i32 s23, s22, 31
	v_lshlrev_b64 v[2:3], 11, v[0:1]
	v_ashrrev_i32_e32 v5, 31, v4
	v_lshl_or_b32 v1, s36, 18, v143
	v_lshl_add_u64 v[2:3], v[4:5], 1, v[2:3]
	v_lshl_or_b32 v208, s37, 14, v1
	v_lshl_or_b32 v1, s36, 9, v216
	s_lshl_b64 s[22:23], s[22:23], 1
	v_lshl_add_u64 v[112:113], s[0:1], 0, v[2:3]
	v_or_b32_e32 v1, s25, v1
	v_mov_b64_e32 v[2:3], s[22:23]
	v_lshl_add_u64 v[114:115], v[94:95], 0, v[208:209]
	v_lshlrev_b32_e32 v208, 2, v1
	v_mad_i64_i32 v[0:1], s[22:23], v0, s33, v[2:3]
	v_lshl_add_u64 v[116:117], s[30:31], 0, v[208:209]
	v_lshl_add_u64 v[118:119], v[98:99], 0, v[0:1]
	s_mov_b64 s[24:25], 0
	v_add_u32_e32 v145, s41, v138
	v_lshl_add_u64 v[204:205], v[102:103], 0, s[12:13]
	global_load_dwordx4 v[180:183], v[204:205], off
	v_lshl_add_u64 v[204:205], v[104:105], 0, s[12:13]
	global_load_dwordx4 v[184:187], v[204:205], off
	v_lshl_add_u64 v[204:205], v[106:107], 0, s[12:13]
	global_load_dwordx4 v[188:191], v[204:205], off
	v_lshl_add_u64 v[204:205], v[108:109], 0, s[12:13]
	global_load_dwordx4 v[192:195], v[204:205], off
	global_load_dwordx4 v[196:199], v[110:111], off
	global_load_dwordx4 v[200:203], v[110:111], off offset:-16
	s_barrier
	s_branch .LBB0_917
.LBB0_916:
	s_waitcnt vmcnt(8)
	v_lshlrev_b32_e32 v64, 16, v134
	s_waitcnt vmcnt(0)
	s_cmp_lg_u32 s24, 0x30000
	s_cbranch_scc0 .Lgm_nopf
	v_lshl_add_u64 v[204:205], v[102:103], 0, s[28:29]
	v_lshl_add_u64 v[204:205], v[204:205], 0, s[12:13]
	global_load_dwordx4 v[180:183], v[204:205], off
	v_lshl_add_u64 v[204:205], v[104:105], 0, s[28:29]
	v_lshl_add_u64 v[204:205], v[204:205], 0, s[12:13]
	global_load_dwordx4 v[184:187], v[204:205], off
	v_lshl_add_u64 v[204:205], v[106:107], 0, s[28:29]
	v_lshl_add_u64 v[204:205], v[204:205], 0, s[12:13]
	global_load_dwordx4 v[188:191], v[204:205], off
	v_lshl_add_u64 v[204:205], v[108:109], 0, s[28:29]
	v_lshl_add_u64 v[204:205], v[204:205], 0, s[12:13]
	global_load_dwordx4 v[192:195], v[204:205], off
	v_lshl_add_u64 v[204:205], v[110:111], 0, s[96:97]
	global_load_dwordx4 v[196:199], v[204:205], off
	global_load_dwordx4 v[200:203], v[204:205], off offset:-16
; DI unsigned cvt_pk_bf16(float lo, float hi) { unsigned r; asm volatile("v_cvt_pk_bf16_f32 %0, %1, %2" : "=v"(r) : "v"(lo), "v"(hi)); return r; }
; DI float bf_lo(unsigned w) { return __uint_as_float(w << 16); }
; DI float bf_hi(unsigned w) { return __uint_as_float(w & 0xffff0000u); }
; DI void gm_unit(const Ctx& cx, const bf16_t* __restrict__ PG, bf16_t* __restrict__ Ogm, const float* __restrict__ gvn, const float* __restrict__ ws, const float* __restrict__ bs, int unit, LAS unsigned char* lds) {
;     ...
;   for (int gi = 0; gi < 4; ++gi) {
;     const int g = gh * 4 + gi;
;     u32x4 vraw[4];
; #pragma unroll
;     for (int it = 0; it < 4; ++it) vraw[it] = *(const u32x4*)(PG + (size_t)(tok0 + srow + 32 * it) * PGW + 4096 + g * 128 + chn * 8);
;     const f32x4 g0 = *(const f32x4*)(gvn + g * 128 + chn * 8), g1 = *(const f32x4*)(gvn + g * 128 + chn * 8 + 4);
;     const float* wrow = ws + ((size_t)g * 128 + t) * 128 + 8 * h;
;     f32x4 wv[8][2];
; #pragma unroll
;     for (int ks = 0; ks < 8; ++ks) if (ks < 4 || tb >= 2) { wv[ks][0] = *(const f32x4*)(wrow + ks * 16); wv[ks][1] = *(const f32x4*)(wrow + ks * 16 + 4); }
;     ...
;     bf16_t* op = Ogm + (size_t)(tok0 + t) * 1024 + g * 128;
; #pragma unroll
;     for (int e = 0; e < 2; ++e)
; #pragma unroll
;       for (int qd = 0; qd < 4; ++qd) { const int d0 = (2 * dbp + e) * 32 + 8 * qd + 4 * h; const u32x2 u2 = uu[e][qd];
;         u32x2 w;
;         w.x = cvt_pk_bf16(bf_lo(u2.x) * (acc[e][4 * qd] + bias), bf_hi(u2.x) * (acc[e][4 * qd + 1] + bias));
;         w.y = cvt_pk_bf16(bf_lo(u2.y) * (acc[e][4 * qd + 2] + bias), bf_hi(u2.y) * (acc[e][4 * qd + 3] + bias));
;         *(u32x2*)(op + d0) = w; }
;     __syncthreads();
.Lgm_nopf:
	s_nop 3
	v_add_f32_e32 v16, v146, v16
	v_mul_f32_e32 v16, v16, v64
	v_and_b32_e32 v64, 0xffff0000, v134
	v_add_f32_e32 v17, v146, v17
	v_mul_f32_e32 v17, v17, v64
	v_cvt_pk_bf16_f32 v16, v16, v17
	v_lshlrev_b32_e32 v17, 16, v135
	v_add_f32_e32 v18, v146, v18
	v_mul_f32_e32 v17, v18, v17
	v_and_b32_e32 v18, 0xffff0000, v135
	v_add_f32_e32 v19, v146, v19
	v_mul_f32_e32 v18, v19, v18
	v_cvt_pk_bf16_f32 v17, v17, v18
	v_lshl_add_u64 v[18:19], v[112:113], 0, s[12:13]
	global_store_dwordx2 v[18:19], v[16:17], off offset:-64
	v_lshlrev_b32_e32 v16, 16, v132
	v_add_f32_e32 v17, v146, v20
	v_mul_f32_e32 v16, v17, v16
	v_and_b32_e32 v17, 0xffff0000, v132
	v_add_f32_e32 v20, v146, v21
	v_mul_f32_e32 v17, v20, v17
	v_cvt_pk_bf16_f32 v16, v16, v17
	v_lshlrev_b32_e32 v17, 16, v133
	v_add_f32_e32 v20, v146, v22
	v_mul_f32_e32 v17, v20, v17
	v_and_b32_e32 v20, 0xffff0000, v133
	v_add_f32_e32 v21, v146, v23
	v_mul_f32_e32 v20, v21, v20
	v_cvt_pk_bf16_f32 v17, v17, v20
	global_store_dwordx2 v[18:19], v[16:17], off offset:-48
	v_lshlrev_b32_e32 v16, 16, v130
	v_add_f32_e32 v17, v146, v24
	v_mul_f32_e32 v16, v17, v16
	v_and_b32_e32 v17, 0xffff0000, v130
	v_add_f32_e32 v20, v146, v25
	v_mul_f32_e32 v17, v20, v17
	v_cvt_pk_bf16_f32 v16, v16, v17
	v_lshlrev_b32_e32 v17, 16, v131
	v_add_f32_e32 v20, v146, v26
	v_mul_f32_e32 v17, v20, v17
	v_and_b32_e32 v20, 0xffff0000, v131
	v_add_f32_e32 v21, v146, v27
	v_mul_f32_e32 v20, v21, v20
	v_cvt_pk_bf16_f32 v17, v17, v20
	global_store_dwordx2 v[18:19], v[16:17], off offset:-32
	v_lshlrev_b32_e32 v16, 16, v128
	v_add_f32_e32 v17, v146, v28
	v_mul_f32_e32 v16, v17, v16
	v_and_b32_e32 v17, 0xffff0000, v128
	v_add_f32_e32 v20, v146, v29
	v_mul_f32_e32 v17, v20, v17
	v_cvt_pk_bf16_f32 v16, v16, v17
	v_lshlrev_b32_e32 v17, 16, v129
	v_add_f32_e32 v20, v146, v30
	v_mul_f32_e32 v17, v20, v17
	v_and_b32_e32 v20, 0xffff0000, v129
	v_add_f32_e32 v21, v146, v31
	v_mul_f32_e32 v20, v21, v20
	v_cvt_pk_bf16_f32 v17, v17, v20
	global_store_dwordx2 v[18:19], v[16:17], off offset:-16
	v_lshlrev_b32_e32 v16, 16, v126
	v_add_f32_e32 v0, v146, v0
	v_mul_f32_e32 v0, v0, v16
	v_and_b32_e32 v16, 0xffff0000, v126
	v_add_f32_e32 v1, v146, v1
	v_mul_f32_e32 v1, v1, v16
	v_cvt_pk_bf16_f32 v0, v0, v1
	v_lshlrev_b32_e32 v1, 16, v127
	v_add_f32_e32 v2, v146, v2
	v_mul_f32_e32 v1, v2, v1
	v_and_b32_e32 v2, 0xffff0000, v127
	v_add_f32_e32 v3, v146, v3
	v_mul_f32_e32 v2, v3, v2
	v_cvt_pk_bf16_f32 v1, v1, v2
	global_store_dwordx2 v[18:19], v[0:1], off
	v_lshlrev_b32_e32 v0, 16, v124
	v_add_f32_e32 v1, v146, v4
	v_mul_f32_e32 v0, v1, v0
	v_and_b32_e32 v1, 0xffff0000, v124
	v_add_f32_e32 v2, v146, v5
	v_mul_f32_e32 v1, v2, v1
	v_cvt_pk_bf16_f32 v0, v0, v1
	v_lshlrev_b32_e32 v1, 16, v125
	v_add_f32_e32 v2, v146, v6
	v_mul_f32_e32 v1, v2, v1
	v_and_b32_e32 v2, 0xffff0000, v125
	v_add_f32_e32 v3, v146, v7
	v_mul_f32_e32 v2, v3, v2
	v_cvt_pk_bf16_f32 v1, v1, v2
	global_store_dwordx2 v[18:19], v[0:1], off offset:16
	v_lshlrev_b32_e32 v0, 16, v122
	v_add_f32_e32 v1, v146, v8
	v_mul_f32_e32 v0, v1, v0
	v_and_b32_e32 v1, 0xffff0000, v122
	v_add_f32_e32 v2, v146, v9
	v_mul_f32_e32 v1, v2, v1
	v_cvt_pk_bf16_f32 v0, v0, v1
	v_lshlrev_b32_e32 v1, 16, v123
	v_add_f32_e32 v2, v146, v10
	v_mul_f32_e32 v1, v2, v1
	v_and_b32_e32 v2, 0xffff0000, v123
	v_add_f32_e32 v3, v146, v11
	v_mul_f32_e32 v2, v3, v2
	v_cvt_pk_bf16_f32 v1, v1, v2
	global_store_dwordx2 v[18:19], v[0:1], off offset:32
	v_lshlrev_b32_e32 v0, 16, v120
	v_add_f32_e32 v1, v146, v12
	v_mul_f32_e32 v0, v1, v0
	v_and_b32_e32 v1, 0xffff0000, v120
	v_add_f32_e32 v2, v146, v13
	v_mul_f32_e32 v1, v2, v1
	s_add_u32 s24, s24, 0x10000
	v_cvt_pk_bf16_f32 v0, v0, v1
	v_lshlrev_b32_e32 v1, 16, v121
	v_add_f32_e32 v2, v146, v14
	s_addc_u32 s25, s25, 0
	v_mul_f32_e32 v1, v2, v1
	v_and_b32_e32 v2, 0xffff0000, v121
	v_add_f32_e32 v3, v146, v15
	v_lshl_add_u64 v[112:113], v[112:113], 0, s[28:29]
	v_lshl_add_u64 v[116:117], v[116:117], 0, s[96:97]
	v_lshl_add_u64 v[102:103], v[102:103], 0, s[28:29]
	v_lshl_add_u64 v[104:105], v[104:105], 0, s[28:29]
	v_lshl_add_u64 v[106:107], v[106:107], 0, s[28:29]
	v_lshl_add_u64 v[108:109], v[108:109], 0, s[28:29]
	v_lshl_add_u64 v[118:119], v[118:119], 0, s[28:29]
	s_cmp_lg_u32 s24, 0x40000
	v_lshl_add_u64 v[110:111], v[110:111], 0, s[96:97]
	v_mul_f32_e32 v2, v3, v2
	v_cvt_pk_bf16_f32 v1, v1, v2
	global_store_dwordx2 v[18:19], v[0:1], off offset:48
	s_barrier
	s_cbranch_scc0 .LBB0_910
.LBB0_917:
	v_lshl_add_u64 v[120:121], v[114:115], 0, s[24:25]
	s_nop 0
	global_load_dwordx4 v[0:3], v[120:121], off offset:16
	global_load_dwordx4 v[4:7], v[120:121], off
	global_load_dwordx4 v[80:83], v[120:121], off offset:80
	global_load_dwordx4 v[84:87], v[120:121], off offset:64
	global_load_dwordx4 v[72:75], v[120:121], off offset:144
	global_load_dwordx4 v[76:79], v[120:121], off offset:128
	global_load_dwordx4 v[64:67], v[120:121], off offset:208
	global_load_dwordx4 v[68:71], v[120:121], off offset:192
	v_cndmask_b32_e64 v122, 0, 1, s[38:39]
	v_cmp_ne_u32_e64 s[36:37], 1, v122
	s_andn2_b64 vcc, exec, s[38:39]
	s_cbranch_vccz .LBB0_926
	s_and_b64 vcc, exec, s[36:37]
	s_cbranch_vccz .LBB0_927

; #define LAS __attribute__((address_space(3)))
; DI unsigned cvt_pk_bf16(float lo, float hi) { unsigned r; asm volatile("v_cvt_pk_bf16_f32 %0, %1, %2" : "=v"(r) : "v"(lo), "v"(hi)); return r; }
; DI float bf_lo(unsigned w) { return __uint_as_float(w << 16); }
; DI float bf_hi(unsigned w) { return __uint_as_float(w & 0xffff0000u); }
; DI void gm_unit(const Ctx& cx, const bf16_t* __restrict__ PG, bf16_t* __restrict__ Ogm, const float* __restrict__ gvn, const float* __restrict__ ws, const float* __restrict__ bs, int unit, LAS unsigned char* lds) {
;     ...
;       for (int qd = 0; qd < 4; ++qd) uu[e][qd] = *(const u32x2*)(up_ + (2 * dbp + e) * 32 + 8 * qd + 4 * h);
;     const float bias = bs[g * 128 + t];
; #pragma unroll
;     for (int it = 0; it < 4; ++it) { const int s = srow + 32 * it; const u32x4 w = vraw[it]; const float ri = rinv[s];
;       u32x4 o;
;       o.x = cvt_pk_bf16(bf_lo(w.x) * ri * g0.x, bf_hi(w.x) * ri * g0.y);
;       o.y = cvt_pk_bf16(bf_lo(w.y) * ri * g0.z, bf_hi(w.y) * ri * g0.w);
;       o.z = cvt_pk_bf16(bf_lo(w.z) * ri * g1.x, bf_hi(w.z) * ri * g1.y);
;       o.w = cvt_pk_bf16(bf_lo(w.w) * ri * g1.z, bf_hi(w.w) * ri * g1.w);
;       *(LAS u32x4*)(lds + s * 320 + chn * 16) = o; }
;     __syncthreads();
.LBB0_922:
	v_lshl_add_u64 v[120:121], v[118:119], 0, s[12:13]
	global_load_dwordx2 v[134:135], v[120:121], off offset:-64
	global_load_dwordx2 v[132:133], v[120:121], off offset:-48
	global_load_dwordx2 v[130:131], v[120:121], off offset:-32
	global_load_dwordx2 v[128:129], v[120:121], off offset:-16
	ds_read_b32 v147, v139 offset:49152
	s_waitcnt vmcnt(12)
	v_mov_b32_e32 v28, v180
	v_mov_b32_e32 v29, v181
	v_mov_b32_e32 v30, v182
	v_mov_b32_e32 v31, v183
	v_mov_b32_e32 v24, v184
	v_mov_b32_e32 v25, v185
	v_mov_b32_e32 v26, v186
	v_mov_b32_e32 v27, v187
	v_mov_b32_e32 v20, v188
	v_mov_b32_e32 v21, v189
	v_mov_b32_e32 v22, v190
	v_mov_b32_e32 v23, v191
	v_mov_b32_e32 v12, v192
	v_mov_b32_e32 v13, v193
	v_mov_b32_e32 v14, v194
	v_mov_b32_e32 v15, v195
	v_mov_b32_e32 v8, v196
	v_mov_b32_e32 v9, v197
	v_mov_b32_e32 v10, v198
	v_mov_b32_e32 v11, v199
	v_mov_b32_e32 v16, v200
	v_mov_b32_e32 v17, v201
	v_mov_b32_e32 v18, v202
	v_mov_b32_e32 v19, v203
	v_lshlrev_b32_e32 v148, 16, v28
	v_and_b32_e32 v28, 0xffff0000, v28
	global_load_dwordx2 v[126:127], v[120:121], off
	global_load_dwordx2 v[124:125], v[120:121], off offset:16
	global_load_dwordx2 v[122:123], v[120:121], off offset:32
	s_nop 0
	global_load_dwordx2 v[120:121], v[120:121], off offset:48
	s_nop 0
	global_load_dword v146, v[116:117], off
	s_and_b64 vcc, exec, s[36:37]
	s_waitcnt lgkmcnt(0)
	v_mul_f32_e32 v148, v147, v148
	v_mul_f32_e32 v28, v147, v28
	s_waitcnt vmcnt(17)
	v_mul_f32_e32 v148, v16, v148
	v_mul_f32_e32 v28, v17, v28
	v_cvt_pk_bf16_f32 v28, v148, v28
	v_lshlrev_b32_e32 v148, 16, v29
	v_and_b32_e32 v29, 0xffff0000, v29
	v_mul_f32_e32 v148, v147, v148
	v_mul_f32_e32 v29, v147, v29
	v_mul_f32_e32 v148, v18, v148
	v_mul_f32_e32 v29, v19, v29
	v_cvt_pk_bf16_f32 v29, v148, v29
	v_lshlrev_b32_e32 v148, 16, v30
	v_and_b32_e32 v30, 0xffff0000, v30
	v_mul_f32_e32 v148, v147, v148
	v_mul_f32_e32 v30, v147, v30
	v_mul_f32_e32 v148, v8, v148
	v_mul_f32_e32 v30, v9, v30
	v_cvt_pk_bf16_f32 v30, v148, v30
	v_lshlrev_b32_e32 v148, 16, v31
	v_and_b32_e32 v31, 0xffff0000, v31
	v_mul_f32_e32 v31, v147, v31
	v_mul_f32_e32 v148, v147, v148
	v_mul_f32_e32 v31, v11, v31
	v_mul_f32_e32 v148, v10, v148
	v_cvt_pk_bf16_f32 v31, v148, v31
	ds_write_b128 v144, v[28:31]
	ds_read_b32 v28, v139 offset:49280
	v_lshlrev_b32_e32 v29, 16, v24
	v_and_b32_e32 v24, 0xffff0000, v24
	s_waitcnt lgkmcnt(0)
	v_mul_f32_e32 v29, v28, v29
	v_mul_f32_e32 v24, v28, v24
	v_mul_f32_e32 v29, v16, v29
	v_mul_f32_e32 v24, v17, v24
	v_cvt_pk_bf16_f32 v24, v29, v24
	v_lshlrev_b32_e32 v29, 16, v25
	v_and_b32_e32 v25, 0xffff0000, v25
	v_mul_f32_e32 v29, v28, v29
	v_mul_f32_e32 v25, v28, v25
	v_mul_f32_e32 v29, v18, v29
	v_mul_f32_e32 v25, v19, v25
	v_cvt_pk_bf16_f32 v25, v29, v25
	v_lshlrev_b32_e32 v29, 16, v26
	v_and_b32_e32 v26, 0xffff0000, v26
	v_mul_f32_e32 v29, v28, v29
	v_mul_f32_e32 v26, v28, v26
	v_mul_f32_e32 v29, v8, v29
	v_mul_f32_e32 v26, v9, v26
	v_cvt_pk_bf16_f32 v26, v29, v26
	v_lshlrev_b32_e32 v29, 16, v27
	v_and_b32_e32 v27, 0xffff0000, v27
	v_mul_f32_e32 v27, v28, v27
	v_mul_f32_e32 v29, v28, v29
	v_mul_f32_e32 v27, v11, v27
	v_mul_f32_e32 v29, v10, v29
	v_cvt_pk_bf16_f32 v27, v29, v27
	ds_write_b128 v144, v[24:27] offset:10240
	ds_read_b32 v24, v139 offset:49408
	v_lshlrev_b32_e32 v25, 16, v20
	v_and_b32_e32 v20, 0xffff0000, v20
	s_waitcnt lgkmcnt(0)
	v_mul_f32_e32 v25, v24, v25
	v_mul_f32_e32 v20, v24, v20
	v_mul_f32_e32 v25, v16, v25
	v_mul_f32_e32 v20, v17, v20
	v_cvt_pk_bf16_f32 v20, v25, v20
	v_lshlrev_b32_e32 v25, 16, v21
	v_and_b32_e32 v21, 0xffff0000, v21
	v_mul_f32_e32 v25, v24, v25
	v_mul_f32_e32 v21, v24, v21
	v_mul_f32_e32 v25, v18, v25
	v_mul_f32_e32 v21, v19, v21
	v_cvt_pk_bf16_f32 v21, v25, v21
	v_lshlrev_b32_e32 v25, 16, v22
	v_and_b32_e32 v22, 0xffff0000, v22
	v_mul_f32_e32 v25, v24, v25
	v_mul_f32_e32 v22, v24, v22
	v_mul_f32_e32 v25, v8, v25
	v_mul_f32_e32 v22, v9, v22
	v_cvt_pk_bf16_f32 v22, v25, v22
	v_lshlrev_b32_e32 v25, 16, v23
	v_and_b32_e32 v23, 0xffff0000, v23
	v_mul_f32_e32 v23, v24, v23
	v_mul_f32_e32 v25, v24, v25
	v_mul_f32_e32 v23, v11, v23
	v_mul_f32_e32 v25, v10, v25
	v_cvt_pk_bf16_f32 v23, v25, v23
	ds_write_b128 v144, v[20:23] offset:20480
	ds_read_b32 v20, v139 offset:49536
	v_lshlrev_b32_e32 v21, 16, v12
	v_and_b32_e32 v12, 0xffff0000, v12
	s_waitcnt lgkmcnt(0)
	v_mul_f32_e32 v21, v20, v21
	v_mul_f32_e32 v12, v20, v12
	v_mul_f32_e32 v16, v16, v21
	v_mul_f32_e32 v12, v17, v12
	v_cvt_pk_bf16_f32 v12, v16, v12
	v_lshlrev_b32_e32 v16, 16, v13
	v_and_b32_e32 v13, 0xffff0000, v13
	v_mul_f32_e32 v16, v20, v16
	v_mul_f32_e32 v13, v20, v13
	v_mul_f32_e32 v16, v18, v16
	v_mul_f32_e32 v13, v19, v13
	v_cvt_pk_bf16_f32 v13, v16, v13
	v_lshlrev_b32_e32 v16, 16, v14
	v_and_b32_e32 v14, 0xffff0000, v14
	v_mul_f32_e32 v16, v20, v16
	v_mul_f32_e32 v14, v20, v14
	v_mul_f32_e32 v8, v8, v16
	v_mul_f32_e32 v9, v9, v14
	v_cvt_pk_bf16_f32 v14, v8, v9
	v_lshlrev_b32_e32 v8, 16, v15
	v_and_b32_e32 v9, 0xffff0000, v15
	v_mul_f32_e32 v8, v20, v8
	v_mul_f32_e32 v9, v20, v9
	v_mul_f32_e32 v8, v10, v8
	v_mul_f32_e32 v9, v11, v9
	v_cvt_pk_bf16_f32 v15, v8, v9
	ds_write_b128 v144, v[12:15] offset:30720
	s_waitcnt lgkmcnt(0)
	s_barrier
; #define MFMA32(a, b, c) __builtin_amdgcn_mfma_f32_32x32x16_bf16((a), (b), (c), 0, 0, 0)
; DI void gm_unit(const Ctx& cx, const bf16_t* __restrict__ PG, bf16_t* __restrict__ Ogm, const float* __restrict__ gvn, const float* __restrict__ ws, const float* __restrict__ bs, int unit, LAS unsigned char* lds) {
;     ...
;     for (int ks = 0; ks < 8; ++ks) if (ks < 4 || tb >= 2) {
;       const bf16x8 bfrag = pack8(wv[ks][0].x, wv[ks][0].y, wv[ks][0].z, wv[ks][0].w, wv[ks][1].x, wv[ks][1].y, wv[ks][1].z, wv[ks][1].w);
; #pragma unroll
;       for (int e = 0; e < 2; ++e) { const int db = 2 * dbp + e;
;         const bf16x8 af = tr_pair(trb + (16 * ks) * 320 + db * 64, trb + (16 * ks + 4) * 320 + db * 64);
;         acc[e] = MFMA32(af, bfrag, acc[e]); }
;     }
	s_waitcnt vmcnt(15)
	v_cvt_pk_bf16_f32 v4, v4, v5
	v_cvt_pk_bf16_f32 v5, v6, v7
	v_cvt_pk_bf16_f32 v6, v0, v1
	v_cvt_pk_bf16_f32 v7, v2, v3
	ds_read_b64_tr_b16 v[0:1], v145
	ds_read_b64_tr_b16 v[2:3], v145 offset:1280
	ds_read_b64_tr_b16 v[10:11], v145 offset:1344
	ds_read_b64_tr_b16 v[8:9], v145 offset:64
	s_waitcnt lgkmcnt(2)
	v_mfma_f32_32x32x16_bf16 v[16:31], v[0:3], v[4:7], 0
	s_waitcnt vmcnt(13)
	v_cvt_pk_bf16_f32 v84, v84, v85
	v_cvt_pk_bf16_f32 v85, v86, v87
	v_cvt_pk_bf16_f32 v86, v80, v81
	v_cvt_pk_bf16_f32 v87, v82, v83
	ds_read_b64_tr_b16 v[80:81], v145 offset:5120
	ds_read_b64_tr_b16 v[82:83], v145 offset:6400
	ds_read_b64_tr_b16 v[150:151], v145 offset:6464
	ds_read_b64_tr_b16 v[148:149], v145 offset:5184
	s_waitcnt vmcnt(11)
	v_cvt_pk_bf16_f32 v76, v76, v77
	v_cvt_pk_bf16_f32 v77, v78, v79
	s_waitcnt lgkmcnt(4)
	v_mfma_f32_32x32x16_bf16 v[0:15], v[8:11], v[4:7], 0
	v_cvt_pk_bf16_f32 v78, v72, v73
	v_cvt_pk_bf16_f32 v79, v74, v75
	s_waitcnt lgkmcnt(2)
	v_mfma_f32_32x32x16_bf16 v[16:31], v[80:83], v[84:87], v[16:31]
	ds_read_b64_tr_b16 v[72:73], v145 offset:10240
	ds_read_b64_tr_b16 v[74:75], v145 offset:11520
	ds_read_b64_tr_b16 v[82:83], v145 offset:11584
	ds_read_b64_tr_b16 v[80:81], v145 offset:10304
	s_waitcnt vmcnt(9)
	v_cvt_pk_bf16_f32 v68, v68, v69
	v_cvt_pk_bf16_f32 v69, v70, v71
	v_cvt_pk_bf16_f32 v70, v64, v65
	v_cvt_pk_bf16_f32 v71, v66, v67
	s_waitcnt lgkmcnt(4)
	v_mfma_f32_32x32x16_bf16 v[0:15], v[148:151], v[84:87], v[0:15]
	s_waitcnt lgkmcnt(2)
	v_mfma_f32_32x32x16_bf16 v[16:31], v[72:75], v[76:79], v[16:31]
	ds_read_b64_tr_b16 v[64:65], v145 offset:15360
	ds_read_b64_tr_b16 v[66:67], v145 offset:16640
	ds_read_b64_tr_b16 v[74:75], v145 offset:16704
	ds_read_b64_tr_b16 v[72:73], v145 offset:15424
	s_waitcnt lgkmcnt(4)
	v_mfma_f32_32x32x16_bf16 v[0:15], v[80:83], v[76:79], v[0:15]
	s_waitcnt lgkmcnt(2)
	v_mfma_f32_32x32x16_bf16 v[16:31], v[64:67], v[68:71], v[16:31]
	s_waitcnt lgkmcnt(0)
	v_mfma_f32_32x32x16_bf16 v[0:15], v[72:75], v[68:71], v[0:15]
	s_cbranch_vccz .LBB0_929
	s_and_b64 vcc, exec, s[36:37]
	s_cbranch_vccz .LBB0_930
